# residual epilogue (bf16 steps): xs base loads with default cache policy instead of nt (lines resident for the in-place stores / next norm); on top of v89
# speedup vs baseline: 1.0097x; 1.0097x over previous
; #define PG8_GAS __attribute__((address_space(1)))
; __device__ __forceinline__ unsigned cvtpk(float lo, float hi) { f32x2 v = {lo, hi}; bf16x2_t b = __builtin_convertvector(v, bf16x2_t); return __builtin_bit_cast(unsigned, b); }
; template <class T> __device__ __forceinline__ GAS T* gp(T* p) { return (GAS T*)p; }
;     __device__ __forceinline__ void operator()(const f32x4 (&acc)[2][2][4][2], const Unit& u, int wr, int wc, int fr, int fq) const {
;     ...
;         for (int bj = 0; bj < 2; ++bj)
; #pragma unroll
;             for (int n = 0; n < 2; ++n) gv[bj][n] = (*(const PG8_GAS f32x4*)(gp + col0 + bj * HALF + 4 * n) + 1.0f) * coef;
; #pragma unroll
;         for (int ai = 0; ai < 2; ++ai)
; #pragma unroll
;             for (int m = 0; m < 4; ++m) {
;                 const size_t off = (size_t)(u.pm * BM + ai * HALF + wr * 64 + m * 16 + fr) * 1024 + col0;
; #pragma unroll
;                 for (int bj = 0; bj < 2; ++bj) {
;                     f32x4 b0, b1;
;                     if (basef) { b0 = __builtin_nontemporal_load((const PG8_GAS f32x4*)(basef + off + bj * HALF)); b1 = __builtin_nontemporal_load((const PG8_GAS f32x4*)(basef + off + bj * HALF + 4)); }
;                     else { const u32x4 w = __builtin_nontemporal_load((const PG8_GAS u32x4*)(baseb + off + bj * HALF));
;                         b0 = (f32x4){__uint_as_float(w.x << 16), __uint_as_float(w.x & 0xffff0000u), __uint_as_float(w.y << 16), __uint_as_float(w.y & 0xffff0000u)};
;                         b1 = (f32x4){__uint_as_float(w.z << 16), __uint_as_float(w.z & 0xffff0000u), __uint_as_float(w.w << 16), __uint_as_float(w.w & 0xffff0000u)}; }
;                     const f32x4 o0 = b0 + gv[bj][0] * acc[ai][bj][m][0], o1 = b1 + gv[bj][1] * acc[ai][bj][m][1];
;                     u32x4 w; w.x = cvtpk(o0[0], o0[1]); w.y = cvtpk(o0[2], o0[3]); w.z = cvtpk(o1[0], o1[1]); w.w = cvtpk(o1[2], o1[3]);
;                     __builtin_nontemporal_store(w, (PG8_GAS u32x4*)(out + off + bj * HALF));
.Lres_epi_bf16:
	s_mov_b32 s4, 0x8000
	s_mov_b32 s5, 0
	s_mov_b32 vcc_lo, 0x28000
	s_mov_b32 vcc_hi, 0
	global_load_dwordx4 v[150:153], v[182:183], off
	global_load_dwordx4 v[154:157], v[182:183], off offset:256
	v_lshl_add_u64 v[182:183], v[182:183], 0, s[4:5]
	global_load_dwordx4 v[170:173], v[182:183], off
	global_load_dwordx4 v[184:187], v[182:183], off offset:256
	v_lshl_add_u64 v[182:183], v[182:183], 0, s[4:5]
	global_load_dwordx4 v[188:191], v[182:183], off
	global_load_dwordx4 v[192:195], v[182:183], off offset:256
	v_lshl_add_u64 v[182:183], v[182:183], 0, s[4:5]
	global_load_dwordx4 v[208:211], v[182:183], off
	global_load_dwordx4 v[226:229], v[182:183], off offset:256
	v_lshl_add_u64 v[182:183], v[182:183], 0, vcc
	global_load_dwordx4 v[230:233], v[182:183], off
	global_load_dwordx4 v[234:237], v[182:183], off offset:256
	v_lshl_add_u64 v[182:183], v[182:183], 0, s[4:5]
	global_load_dwordx4 v[238:241], v[182:183], off
	global_load_dwordx4 v[242:245], v[182:183], off offset:256
	v_lshl_add_u64 v[182:183], v[182:183], 0, s[4:5]
	global_load_dwordx4 v[246:249], v[182:183], off
	global_load_dwordx4 v[250:253], v[182:183], off offset:256
	v_lshl_add_u64 v[182:183], v[182:183], 0, s[4:5]
	s_cmp_eq_u64 s[78:79], 0
	s_cbranch_scc1 .Lres_nb_bf16
	s_barrier
.Lres_nb_bf16:
	s_waitcnt vmcnt(13)
	v_pk_add_f32 v[148:149], v[148:149], 1.0 op_sel_hi:[1,0]
	v_pk_add_f32 v[180:181], v[146:147], 1.0 op_sel_hi:[1,0]
	v_pk_mul_f32 v[146:147], s[60:61], v[148:149]
	v_pk_mul_f32 v[148:149], s[10:11], v[180:181]
	v_pk_add_f32 v[180:181], v[142:143], 1.0 op_sel_hi:[1,0]
	v_pk_add_f32 v[142:143], v[144:145], 1.0 op_sel_hi:[1,0]
	v_pk_mul_f32 v[144:145], s[10:11], v[180:181]
	v_pk_mul_f32 v[142:143], s[60:61], v[142:143]
	v_pk_add_f32 v[140:141], v[140:141], 1.0 op_sel_hi:[1,0]
	v_pk_add_f32 v[180:181], v[138:139], 1.0 op_sel_hi:[1,0]
	v_pk_mul_f32 v[138:139], s[60:61], v[140:141]
	v_pk_mul_f32 v[140:141], s[10:11], v[180:181]
	v_pk_add_f32 v[180:181], v[134:135], 1.0 op_sel_hi:[1,0]
	v_pk_add_f32 v[134:135], v[136:137], 1.0 op_sel_hi:[1,0]
	v_pk_mul_f32 v[136:137], s[10:11], v[180:181]
	v_pk_mul_f32 v[134:135], s[60:61], v[134:135]
	v_lshlrev_b32_e32 v180, 16, v150
	v_and_b32_e32 v181, 0xffff0000, v150
	v_pk_fma_f32 v[130:131], v[130:131], v[148:149], v[180:181]
	v_lshlrev_b32_e32 v150, 16, v151
	v_and_b32_e32 v151, 0xffff0000, v151
	v_pk_fma_f32 v[132:133], v[132:133], v[146:147], v[150:151]
	v_lshlrev_b32_e32 v180, 16, v152
	v_and_b32_e32 v181, 0xffff0000, v152
	v_pk_fma_f32 v[126:127], v[126:127], v[144:145], v[180:181]
	v_lshlrev_b32_e32 v152, 16, v153
	v_and_b32_e32 v153, 0xffff0000, v153
	v_pk_fma_f32 v[128:129], v[128:129], v[142:143], v[152:153]
	v_cvt_pk_bf16_f32 v130, v130, v131
	v_cvt_pk_bf16_f32 v131, v132, v133
	v_cvt_pk_bf16_f32 v132, v126, v127
	v_cvt_pk_bf16_f32 v133, v128, v129
	global_load_dwordx4 v[150:153], v[182:183], off
	global_load_dwordx4 v[126:129], v[182:183], off offset:256
	global_store_dwordx4 v[2:3], v[130:133], off
	s_waitcnt vmcnt(15)
	v_lshlrev_b32_e32 v180, 16, v154
	v_and_b32_e32 v181, 0xffff0000, v154
	v_pk_fma_f32 v[122:123], v[122:123], v[140:141], v[180:181]
	v_lshlrev_b32_e32 v154, 16, v155
	v_and_b32_e32 v155, 0xffff0000, v155
	v_pk_fma_f32 v[124:125], v[124:125], v[138:139], v[154:155]
	v_lshlrev_b32_e32 v180, 16, v156
	v_and_b32_e32 v181, 0xffff0000, v156
	v_pk_fma_f32 v[118:119], v[118:119], v[136:137], v[180:181]
	v_lshlrev_b32_e32 v156, 16, v157
	v_and_b32_e32 v157, 0xffff0000, v157
	v_pk_fma_f32 v[120:121], v[120:121], v[134:135], v[156:157]
	v_cvt_pk_bf16_f32 v122, v122, v123
	v_cvt_pk_bf16_f32 v123, v124, v125
	v_cvt_pk_bf16_f32 v124, v118, v119
	v_cvt_pk_bf16_f32 v125, v120, v121
	global_store_dwordx4 v[2:3], v[122:125], off offset:256
	v_lshl_add_u64 v[2:3], v[2:3], 0, s[4:5]
	s_waitcnt vmcnt(15)
	v_lshlrev_b32_e32 v180, 16, v170
	v_and_b32_e32 v181, 0xffff0000, v170
	v_pk_fma_f32 v[114:115], v[114:115], v[148:149], v[180:181]
	v_lshlrev_b32_e32 v170, 16, v171
	v_and_b32_e32 v171, 0xffff0000, v171
	v_pk_fma_f32 v[116:117], v[116:117], v[146:147], v[170:171]
	v_lshlrev_b32_e32 v180, 16, v172
	v_and_b32_e32 v181, 0xffff0000, v172
	v_pk_fma_f32 v[110:111], v[110:111], v[144:145], v[180:181]
	v_lshlrev_b32_e32 v172, 16, v173
	v_and_b32_e32 v173, 0xffff0000, v173
	v_pk_fma_f32 v[112:113], v[112:113], v[142:143], v[172:173]
	v_cvt_pk_bf16_f32 v114, v114, v115
	v_cvt_pk_bf16_f32 v115, v116, v117
	v_cvt_pk_bf16_f32 v116, v110, v111
	v_cvt_pk_bf16_f32 v117, v112, v113
	global_store_dwordx4 v[2:3], v[114:117], off
	s_waitcnt vmcnt(15)
	v_lshlrev_b32_e32 v180, 16, v184
	v_and_b32_e32 v181, 0xffff0000, v184
	v_pk_fma_f32 v[106:107], v[106:107], v[140:141], v[180:181]
	v_lshlrev_b32_e32 v184, 16, v185
	v_and_b32_e32 v185, 0xffff0000, v185
	v_pk_fma_f32 v[108:109], v[108:109], v[138:139], v[184:185]
	v_lshlrev_b32_e32 v180, 16, v186
	v_and_b32_e32 v181, 0xffff0000, v186
	v_pk_fma_f32 v[102:103], v[102:103], v[136:137], v[180:181]
	v_lshlrev_b32_e32 v186, 16, v187
	v_and_b32_e32 v187, 0xffff0000, v187
	v_pk_fma_f32 v[104:105], v[104:105], v[134:135], v[186:187]
	v_cvt_pk_bf16_f32 v106, v106, v107
	v_cvt_pk_bf16_f32 v107, v108, v109
	v_cvt_pk_bf16_f32 v108, v102, v103
	v_cvt_pk_bf16_f32 v109, v104, v105
	global_store_dwordx4 v[2:3], v[106:109], off offset:256
	v_lshl_add_u64 v[2:3], v[2:3], 0, s[4:5]
	s_waitcnt vmcnt(15)
; #define PG8_GAS __attribute__((address_space(1)))
; __device__ __forceinline__ unsigned cvtpk(float lo, float hi) { f32x2 v = {lo, hi}; bf16x2_t b = __builtin_convertvector(v, bf16x2_t); return __builtin_bit_cast(unsigned, b); }
;     __device__ __forceinline__ void operator()(const f32x4 (&acc)[2][2][4][2], const Unit& u, int wr, int wc, int fr, int fq) const {
;     ...
;                 for (int bj = 0; bj < 2; ++bj) {
;                     f32x4 b0, b1;
;                     if (basef) { b0 = __builtin_nontemporal_load((const PG8_GAS f32x4*)(basef + off + bj * HALF)); b1 = __builtin_nontemporal_load((const PG8_GAS f32x4*)(basef + off + bj * HALF + 4)); }
;                     else { const u32x4 w = __builtin_nontemporal_load((const PG8_GAS u32x4*)(baseb + off + bj * HALF));
;                         b0 = (f32x4){__uint_as_float(w.x << 16), __uint_as_float(w.x & 0xffff0000u), __uint_as_float(w.y << 16), __uint_as_float(w.y & 0xffff0000u)};
;                         b1 = (f32x4){__uint_as_float(w.z << 16), __uint_as_float(w.z & 0xffff0000u), __uint_as_float(w.w << 16), __uint_as_float(w.w & 0xffff0000u)}; }
;                     const f32x4 o0 = b0 + gv[bj][0] * acc[ai][bj][m][0], o1 = b1 + gv[bj][1] * acc[ai][bj][m][1];
;                     u32x4 w; w.x = cvtpk(o0[0], o0[1]); w.y = cvtpk(o0[2], o0[3]); w.z = cvtpk(o1[0], o1[1]); w.w = cvtpk(o1[2], o1[3]);
;                     __builtin_nontemporal_store(w, (PG8_GAS u32x4*)(out + off + bj * HALF));
	v_lshlrev_b32_e32 v180, 16, v188
	v_and_b32_e32 v181, 0xffff0000, v188
	v_pk_fma_f32 v[98:99], v[98:99], v[148:149], v[180:181]
	v_lshlrev_b32_e32 v188, 16, v189
	v_and_b32_e32 v189, 0xffff0000, v189
	v_pk_fma_f32 v[100:101], v[100:101], v[146:147], v[188:189]
	v_lshlrev_b32_e32 v180, 16, v190
	v_and_b32_e32 v181, 0xffff0000, v190
	v_pk_fma_f32 v[94:95], v[94:95], v[144:145], v[180:181]
	v_lshlrev_b32_e32 v190, 16, v191
	v_and_b32_e32 v191, 0xffff0000, v191
	v_pk_fma_f32 v[96:97], v[96:97], v[142:143], v[190:191]
	v_cvt_pk_bf16_f32 v98, v98, v99
	v_cvt_pk_bf16_f32 v99, v100, v101
	v_cvt_pk_bf16_f32 v100, v94, v95
	v_cvt_pk_bf16_f32 v101, v96, v97
	global_store_dwordx4 v[2:3], v[98:101], off
	s_waitcnt vmcnt(15)
	v_lshlrev_b32_e32 v180, 16, v192
	v_and_b32_e32 v181, 0xffff0000, v192
	v_pk_fma_f32 v[90:91], v[90:91], v[140:141], v[180:181]
	v_lshlrev_b32_e32 v192, 16, v193
	v_and_b32_e32 v193, 0xffff0000, v193
	v_pk_fma_f32 v[92:93], v[92:93], v[138:139], v[192:193]
	v_lshlrev_b32_e32 v180, 16, v194
	v_and_b32_e32 v181, 0xffff0000, v194
	v_pk_fma_f32 v[86:87], v[86:87], v[136:137], v[180:181]
	v_lshlrev_b32_e32 v194, 16, v195
	v_and_b32_e32 v195, 0xffff0000, v195
	v_pk_fma_f32 v[88:89], v[88:89], v[134:135], v[194:195]
	v_cvt_pk_bf16_f32 v90, v90, v91
	v_cvt_pk_bf16_f32 v91, v92, v93
	v_cvt_pk_bf16_f32 v92, v86, v87
	v_cvt_pk_bf16_f32 v93, v88, v89
	global_store_dwordx4 v[2:3], v[90:93], off offset:256
	v_lshl_add_u64 v[2:3], v[2:3], 0, s[4:5]
	s_waitcnt vmcnt(15)
	v_lshlrev_b32_e32 v180, 16, v208
	v_and_b32_e32 v181, 0xffff0000, v208
	v_pk_fma_f32 v[82:83], v[82:83], v[148:149], v[180:181]
	v_lshlrev_b32_e32 v208, 16, v209
	v_and_b32_e32 v209, 0xffff0000, v209
	v_pk_fma_f32 v[84:85], v[84:85], v[146:147], v[208:209]
	v_lshlrev_b32_e32 v180, 16, v210
	v_and_b32_e32 v181, 0xffff0000, v210
	v_pk_fma_f32 v[78:79], v[78:79], v[144:145], v[180:181]
	v_lshlrev_b32_e32 v210, 16, v211
	v_and_b32_e32 v211, 0xffff0000, v211
	v_pk_fma_f32 v[80:81], v[80:81], v[142:143], v[210:211]
	v_cvt_pk_bf16_f32 v82, v82, v83
	v_cvt_pk_bf16_f32 v83, v84, v85
	v_cvt_pk_bf16_f32 v84, v78, v79
	v_cvt_pk_bf16_f32 v85, v80, v81
	global_store_dwordx4 v[2:3], v[82:85], off
	s_waitcnt vmcnt(15)
	v_lshlrev_b32_e32 v180, 16, v226
	v_and_b32_e32 v181, 0xffff0000, v226
	v_pk_fma_f32 v[74:75], v[74:75], v[140:141], v[180:181]
	v_lshlrev_b32_e32 v226, 16, v227
	v_and_b32_e32 v227, 0xffff0000, v227
	v_pk_fma_f32 v[76:77], v[76:77], v[138:139], v[226:227]
	v_lshlrev_b32_e32 v180, 16, v228
	v_and_b32_e32 v181, 0xffff0000, v228
	v_pk_fma_f32 v[70:71], v[70:71], v[136:137], v[180:181]
	v_lshlrev_b32_e32 v228, 16, v229
	v_and_b32_e32 v229, 0xffff0000, v229
	v_pk_fma_f32 v[72:73], v[72:73], v[134:135], v[228:229]
	v_cvt_pk_bf16_f32 v74, v74, v75
	v_cvt_pk_bf16_f32 v75, v76, v77
	v_cvt_pk_bf16_f32 v76, v70, v71
	v_cvt_pk_bf16_f32 v77, v72, v73
	global_store_dwordx4 v[2:3], v[74:77], off offset:256
	v_lshl_add_u64 v[2:3], v[2:3], 0, vcc
	s_waitcnt vmcnt(15)
	v_lshlrev_b32_e32 v180, 16, v230
	v_and_b32_e32 v181, 0xffff0000, v230
	v_pk_fma_f32 v[66:67], v[66:67], v[148:149], v[180:181]
	v_lshlrev_b32_e32 v230, 16, v231
	v_and_b32_e32 v231, 0xffff0000, v231
	v_pk_fma_f32 v[68:69], v[68:69], v[146:147], v[230:231]
	v_lshlrev_b32_e32 v180, 16, v232
	v_and_b32_e32 v181, 0xffff0000, v232
	v_pk_fma_f32 v[62:63], v[62:63], v[144:145], v[180:181]
	v_lshlrev_b32_e32 v232, 16, v233
	v_and_b32_e32 v233, 0xffff0000, v233
	v_pk_fma_f32 v[64:65], v[64:65], v[142:143], v[232:233]
	v_cvt_pk_bf16_f32 v66, v66, v67
	v_cvt_pk_bf16_f32 v67, v68, v69
	v_cvt_pk_bf16_f32 v68, v62, v63
	v_cvt_pk_bf16_f32 v69, v64, v65
	global_store_dwordx4 v[2:3], v[66:69], off
	s_waitcnt vmcnt(15)
	v_lshlrev_b32_e32 v180, 16, v234
	v_and_b32_e32 v181, 0xffff0000, v234
	v_pk_fma_f32 v[58:59], v[58:59], v[140:141], v[180:181]
	v_lshlrev_b32_e32 v234, 16, v235
	v_and_b32_e32 v235, 0xffff0000, v235
	v_pk_fma_f32 v[60:61], v[60:61], v[138:139], v[234:235]
	v_lshlrev_b32_e32 v180, 16, v236
	v_and_b32_e32 v181, 0xffff0000, v236
	v_pk_fma_f32 v[54:55], v[54:55], v[136:137], v[180:181]
	v_lshlrev_b32_e32 v236, 16, v237
	v_and_b32_e32 v237, 0xffff0000, v237
	v_pk_fma_f32 v[56:57], v[56:57], v[134:135], v[236:237]
	v_cvt_pk_bf16_f32 v58, v58, v59
	v_cvt_pk_bf16_f32 v59, v60, v61
	v_cvt_pk_bf16_f32 v60, v54, v55
	v_cvt_pk_bf16_f32 v61, v56, v57
	global_store_dwordx4 v[2:3], v[58:61], off offset:256
	v_lshl_add_u64 v[2:3], v[2:3], 0, s[4:5]
	s_waitcnt vmcnt(15)
; #define PG8_GAS __attribute__((address_space(1)))
; __device__ __forceinline__ unsigned cvtpk(float lo, float hi) { f32x2 v = {lo, hi}; bf16x2_t b = __builtin_convertvector(v, bf16x2_t); return __builtin_bit_cast(unsigned, b); }
;     __device__ __forceinline__ void operator()(const f32x4 (&acc)[2][2][4][2], const Unit& u, int wr, int wc, int fr, int fq) const {
;     ...
;                 for (int bj = 0; bj < 2; ++bj) {
;                     f32x4 b0, b1;
;                     if (basef) { b0 = __builtin_nontemporal_load((const PG8_GAS f32x4*)(basef + off + bj * HALF)); b1 = __builtin_nontemporal_load((const PG8_GAS f32x4*)(basef + off + bj * HALF + 4)); }
;                     else { const u32x4 w = __builtin_nontemporal_load((const PG8_GAS u32x4*)(baseb + off + bj * HALF));
;                         b0 = (f32x4){__uint_as_float(w.x << 16), __uint_as_float(w.x & 0xffff0000u), __uint_as_float(w.y << 16), __uint_as_float(w.y & 0xffff0000u)};
;                         b1 = (f32x4){__uint_as_float(w.z << 16), __uint_as_float(w.z & 0xffff0000u), __uint_as_float(w.w << 16), __uint_as_float(w.w & 0xffff0000u)}; }
;                     const f32x4 o0 = b0 + gv[bj][0] * acc[ai][bj][m][0], o1 = b1 + gv[bj][1] * acc[ai][bj][m][1];
;                     u32x4 w; w.x = cvtpk(o0[0], o0[1]); w.y = cvtpk(o0[2], o0[3]); w.z = cvtpk(o1[0], o1[1]); w.w = cvtpk(o1[2], o1[3]);
;                     __builtin_nontemporal_store(w, (PG8_GAS u32x4*)(out + off + bj * HALF));
	v_lshlrev_b32_e32 v180, 16, v238
	v_and_b32_e32 v181, 0xffff0000, v238
	v_pk_fma_f32 v[50:51], v[50:51], v[148:149], v[180:181]
	v_lshlrev_b32_e32 v238, 16, v239
	v_and_b32_e32 v239, 0xffff0000, v239
	v_pk_fma_f32 v[52:53], v[52:53], v[146:147], v[238:239]
	v_lshlrev_b32_e32 v180, 16, v240
	v_and_b32_e32 v181, 0xffff0000, v240
	v_pk_fma_f32 v[46:47], v[46:47], v[144:145], v[180:181]
	v_lshlrev_b32_e32 v240, 16, v241
	v_and_b32_e32 v241, 0xffff0000, v241
	v_pk_fma_f32 v[48:49], v[48:49], v[142:143], v[240:241]
	v_cvt_pk_bf16_f32 v50, v50, v51
	v_cvt_pk_bf16_f32 v51, v52, v53
	v_cvt_pk_bf16_f32 v52, v46, v47
	v_cvt_pk_bf16_f32 v53, v48, v49
	global_store_dwordx4 v[2:3], v[50:53], off
	s_waitcnt vmcnt(15)
	v_lshlrev_b32_e32 v180, 16, v242
	v_and_b32_e32 v181, 0xffff0000, v242
	v_pk_fma_f32 v[42:43], v[42:43], v[140:141], v[180:181]
	v_lshlrev_b32_e32 v242, 16, v243
	v_and_b32_e32 v243, 0xffff0000, v243
	v_pk_fma_f32 v[44:45], v[44:45], v[138:139], v[242:243]
	v_lshlrev_b32_e32 v180, 16, v244
	v_and_b32_e32 v181, 0xffff0000, v244
	v_pk_fma_f32 v[38:39], v[38:39], v[136:137], v[180:181]
	v_lshlrev_b32_e32 v244, 16, v245
	v_and_b32_e32 v245, 0xffff0000, v245
	v_pk_fma_f32 v[40:41], v[40:41], v[134:135], v[244:245]
	v_cvt_pk_bf16_f32 v42, v42, v43
	v_cvt_pk_bf16_f32 v43, v44, v45
	v_cvt_pk_bf16_f32 v44, v38, v39
	v_cvt_pk_bf16_f32 v45, v40, v41
	global_store_dwordx4 v[2:3], v[42:45], off offset:256
	v_lshl_add_u64 v[2:3], v[2:3], 0, s[4:5]
	s_waitcnt vmcnt(15)
	v_lshlrev_b32_e32 v180, 16, v246
	v_and_b32_e32 v181, 0xffff0000, v246
	v_pk_fma_f32 v[34:35], v[34:35], v[148:149], v[180:181]
	v_lshlrev_b32_e32 v246, 16, v247
	v_and_b32_e32 v247, 0xffff0000, v247
	v_pk_fma_f32 v[36:37], v[36:37], v[146:147], v[246:247]
	v_lshlrev_b32_e32 v180, 16, v248
	v_and_b32_e32 v181, 0xffff0000, v248
	v_pk_fma_f32 v[30:31], v[30:31], v[144:145], v[180:181]
	v_lshlrev_b32_e32 v248, 16, v249
	v_and_b32_e32 v249, 0xffff0000, v249
	v_pk_fma_f32 v[32:33], v[32:33], v[142:143], v[248:249]
	v_cvt_pk_bf16_f32 v34, v34, v35
	v_cvt_pk_bf16_f32 v35, v36, v37
	v_cvt_pk_bf16_f32 v36, v30, v31
	v_cvt_pk_bf16_f32 v37, v32, v33
	global_store_dwordx4 v[2:3], v[34:37], off
	s_waitcnt vmcnt(15)
	v_lshlrev_b32_e32 v180, 16, v250
	v_and_b32_e32 v181, 0xffff0000, v250
	v_pk_fma_f32 v[26:27], v[26:27], v[140:141], v[180:181]
	v_lshlrev_b32_e32 v250, 16, v251
	v_and_b32_e32 v251, 0xffff0000, v251
	v_pk_fma_f32 v[28:29], v[28:29], v[138:139], v[250:251]
	v_lshlrev_b32_e32 v180, 16, v252
	v_and_b32_e32 v181, 0xffff0000, v252
	v_pk_fma_f32 v[22:23], v[22:23], v[136:137], v[180:181]
	v_lshlrev_b32_e32 v252, 16, v253
	v_and_b32_e32 v253, 0xffff0000, v253
	v_pk_fma_f32 v[24:25], v[24:25], v[134:135], v[252:253]
	v_cvt_pk_bf16_f32 v26, v26, v27
	v_cvt_pk_bf16_f32 v27, v28, v29
	v_cvt_pk_bf16_f32 v28, v22, v23
	v_cvt_pk_bf16_f32 v29, v24, v25
	global_store_dwordx4 v[2:3], v[26:29], off offset:256
	v_lshl_add_u64 v[2:3], v[2:3], 0, s[4:5]
	s_waitcnt vmcnt(15)
	v_lshlrev_b32_e32 v180, 16, v150
	v_and_b32_e32 v181, 0xffff0000, v150
	v_pk_fma_f32 v[18:19], v[18:19], v[148:149], v[180:181]
	v_lshlrev_b32_e32 v150, 16, v151
	v_and_b32_e32 v151, 0xffff0000, v151
	v_pk_fma_f32 v[20:21], v[20:21], v[146:147], v[150:151]
	v_lshlrev_b32_e32 v180, 16, v152
	v_and_b32_e32 v181, 0xffff0000, v152
	v_pk_fma_f32 v[14:15], v[14:15], v[144:145], v[180:181]
	v_lshlrev_b32_e32 v152, 16, v153
	v_and_b32_e32 v153, 0xffff0000, v153
	v_pk_fma_f32 v[16:17], v[16:17], v[142:143], v[152:153]
	v_cvt_pk_bf16_f32 v18, v18, v19
	v_cvt_pk_bf16_f32 v19, v20, v21
	v_cvt_pk_bf16_f32 v20, v14, v15
	v_cvt_pk_bf16_f32 v21, v16, v17
	global_store_dwordx4 v[2:3], v[18:21], off
	s_waitcnt vmcnt(15)
	v_lshlrev_b32_e32 v180, 16, v126
	v_and_b32_e32 v181, 0xffff0000, v126
	v_pk_fma_f32 v[10:11], v[10:11], v[140:141], v[180:181]
	v_lshlrev_b32_e32 v126, 16, v127
	v_and_b32_e32 v127, 0xffff0000, v127
	v_pk_fma_f32 v[12:13], v[12:13], v[138:139], v[126:127]
	v_lshlrev_b32_e32 v180, 16, v128
	v_and_b32_e32 v181, 0xffff0000, v128
	v_pk_fma_f32 v[6:7], v[6:7], v[136:137], v[180:181]
	v_lshlrev_b32_e32 v128, 16, v129
	v_and_b32_e32 v129, 0xffff0000, v129
	v_pk_fma_f32 v[8:9], v[8:9], v[134:135], v[128:129]
	v_cvt_pk_bf16_f32 v10, v10, v11
	v_cvt_pk_bf16_f32 v11, v12, v13
	v_cvt_pk_bf16_f32 v12, v6, v7
	v_cvt_pk_bf16_f32 v13, v8, v9
	s_and_b64 vcc, exec, s[6:7]
	s_mov_b64 s[4:5], -1
	global_store_dwordx4 v[2:3], v[10:13], off offset:256
